# SwiGLU epilogue ACT stores sc1 (write-through, keeps A/B tiles in L2)
# speedup vs baseline: 1.0227x; 1.0075x over previous
.LBB0_900:
	s_waitcnt lgkmcnt(0)
	v_pk_mul_f32 v[130:131], v[130:131], v[172:173] op_sel_hi:[1,0]
	v_pk_mul_f32 v[126:127], v[126:127], v[172:173] op_sel_hi:[1,0]
	v_mul_f32_e32 v135, 0xbfb8aa3b, v130
	v_exp_f32_e32 v135, v135
	v_pk_mul_f32 v[128:129], v[128:129], v[172:173] op_sel_hi:[1,0]
	v_pk_mul_f32 v[122:123], v[122:123], v[172:173] op_sel_hi:[1,0]
	v_pk_mul_f32 v[118:119], v[118:119], v[172:173] op_sel_hi:[1,0]
	v_add_f32_e32 v135, 1.0, v135
	v_rcp_f32_e32 v184, v135
	v_mul_f32_e32 v135, 0xbfb8aa3b, v131
	v_exp_f32_e32 v135, v135
	v_lshl_or_b32 v136, s35, 7, v173
	v_ashrrev_i32_e32 v137, 31, v136
	v_lshl_add_u64 v[136:137], v[136:137], 1, s[66:67]
	v_add_f32_e32 v135, 1.0, v135
	v_rcp_f32_e32 v185, v135
	v_pk_mul_f32 v[120:121], v[120:121], v[172:173] op_sel_hi:[1,0]
	v_pk_mul_f32 v[114:115], v[114:115], v[170:171] op_sel_hi:[1,0]
	v_pk_mul_f32 v[110:111], v[110:111], v[170:171] op_sel_hi:[1,0]
	v_pk_mul_f32 v[130:131], v[130:131], v[184:185]
	v_pk_mul_f32 v[112:113], v[112:113], v[170:171] op_sel_hi:[1,0]
	v_pk_mul_f32 v[126:127], v[126:127], v[130:131]
	v_pk_mul_f32 v[130:131], v[132:133], v[172:173] op_sel_hi:[1,0]
	v_pk_mul_f32 v[106:107], v[106:107], v[170:171] op_sel_hi:[1,0]
	v_mul_f32_e32 v132, 0xbfb8aa3b, v130
	v_mul_f32_e32 v133, 0xbfb8aa3b, v131
	v_exp_f32_e32 v132, v132
	v_exp_f32_e32 v133, v133
	v_pk_mul_f32 v[102:103], v[102:103], v[170:171] op_sel_hi:[1,0]
	v_pk_mul_f32 v[104:105], v[104:105], v[170:171] op_sel_hi:[1,0]
	v_add_f32_e32 v132, 1.0, v132
	v_add_f32_e32 v133, 1.0, v133
	v_rcp_f32_e32 v132, v132
	v_rcp_f32_e32 v133, v133
	v_pk_mul_f32 v[98:99], v[98:99], v[168:169] op_sel_hi:[1,0]
	v_pk_mul_f32 v[94:95], v[94:95], v[168:169] op_sel_hi:[1,0]
	v_pk_mul_f32 v[96:97], v[96:97], v[168:169] op_sel_hi:[1,0]
	v_pk_mul_f32 v[130:131], v[130:131], v[132:133]
	v_pk_mul_f32 v[90:91], v[90:91], v[168:169] op_sel_hi:[1,0]
	v_pk_mul_f32 v[128:129], v[128:129], v[130:131]
	v_mul_f32_e32 v130, 0xbfb8aa3b, v122
	v_mul_f32_e32 v131, 0xbfb8aa3b, v123
	v_exp_f32_e32 v130, v130
	v_exp_f32_e32 v131, v131
	v_pk_mul_f32 v[86:87], v[86:87], v[168:169] op_sel_hi:[1,0]
	v_pk_mul_f32 v[88:89], v[88:89], v[168:169] op_sel_hi:[1,0]
	v_add_f32_e32 v130, 1.0, v130
	v_add_f32_e32 v131, 1.0, v131
	v_rcp_f32_e32 v130, v130
	v_rcp_f32_e32 v131, v131
	v_pk_mul_f32 v[82:83], v[82:83], v[164:165] op_sel_hi:[1,0]
	v_pk_mul_f32 v[78:79], v[78:79], v[164:165] op_sel_hi:[1,0]
	v_pk_mul_f32 v[80:81], v[80:81], v[164:165] op_sel_hi:[1,0]
	v_pk_mul_f32 v[122:123], v[122:123], v[130:131]
	v_mad_u64_u32 v[130:131], s[2:3], v162, s78, v[136:137]
	v_pk_mul_f32 v[122:123], v[118:119], v[122:123]
	v_pk_mul_f32 v[118:119], v[124:125], v[172:173] op_sel_hi:[1,0]
	v_pk_mul_f32 v[74:75], v[74:75], v[164:165] op_sel_hi:[1,0]
	v_mul_f32_e32 v124, 0xbfb8aa3b, v118
	v_mul_f32_e32 v125, 0xbfb8aa3b, v119
	v_exp_f32_e32 v124, v124
	v_exp_f32_e32 v125, v125
	v_pk_mul_f32 v[70:71], v[70:71], v[164:165] op_sel_hi:[1,0]
	v_pk_mul_f32 v[72:73], v[72:73], v[164:165] op_sel_hi:[1,0]
	v_add_f32_e32 v124, 1.0, v124
	v_add_f32_e32 v125, 1.0, v125
	v_rcp_f32_e32 v124, v124
	v_rcp_f32_e32 v125, v125
	v_pk_mul_f32 v[66:67], v[66:67], v[166:167] op_sel_hi:[1,0]
	v_pk_mul_f32 v[62:63], v[62:63], v[166:167] op_sel_hi:[1,0]
	v_pk_mul_f32 v[64:65], v[64:65], v[166:167] op_sel_hi:[1,0]
	v_pk_mul_f32 v[118:119], v[118:119], v[124:125]
	v_pk_mul_f32 v[58:59], v[58:59], v[166:167] op_sel_hi:[1,0]
	v_pk_mul_f32 v[124:125], v[120:121], v[118:119]
	v_mov_b32_e32 v118, v131
	v_mad_u64_u32 v[118:119], s[2:3], v163, s78, v[118:119]
	v_mov_b32_e32 v131, v118
	v_cvt_pk_bf16_f32 v118, v126, v127
	v_cvt_pk_bf16_f32 v119, v128, v129
	v_cvt_pk_bf16_f32 v120, v122, v123
	v_cvt_pk_bf16_f32 v121, v124, v125
	global_store_dwordx4 v[130:131], v[118:121], off sc1
	v_pk_mul_f32 v[54:55], v[54:55], v[166:167] op_sel_hi:[1,0]
	v_pk_mul_f32 v[56:57], v[56:57], v[166:167] op_sel_hi:[1,0]
	v_mul_f32_e32 v118, 0xbfb8aa3b, v114
	v_mul_f32_e32 v119, 0xbfb8aa3b, v115
	v_exp_f32_e32 v118, v118
	v_exp_f32_e32 v119, v119
	v_pk_mul_f32 v[50:51], v[50:51], v[174:175] op_sel_hi:[1,0]
	v_pk_mul_f32 v[46:47], v[46:47], v[174:175] op_sel_hi:[1,0]
	v_add_f32_e32 v118, 1.0, v118
	v_add_f32_e32 v119, 1.0, v119
	v_rcp_f32_e32 v118, v118
	v_rcp_f32_e32 v119, v119
	v_pk_mul_f32 v[48:49], v[48:49], v[174:175] op_sel_hi:[1,0]
	v_pk_mul_f32 v[42:43], v[42:43], v[174:175] op_sel_hi:[1,0]
	v_pk_mul_f32 v[38:39], v[38:39], v[174:175] op_sel_hi:[1,0]
	v_pk_mul_f32 v[114:115], v[114:115], v[118:119]
	v_pk_mul_f32 v[40:41], v[40:41], v[174:175] op_sel_hi:[1,0]
	v_pk_mul_f32 v[110:111], v[110:111], v[114:115]
	v_pk_mul_f32 v[114:115], v[116:117], v[170:171] op_sel_hi:[1,0]
	v_pk_mul_f32 v[34:35], v[34:35], v[182:183] op_sel_hi:[1,0]
	v_mul_f32_e32 v116, 0xbfb8aa3b, v114
	v_mul_f32_e32 v117, 0xbfb8aa3b, v115
	v_exp_f32_e32 v116, v116
	v_exp_f32_e32 v117, v117
	v_pk_mul_f32 v[30:31], v[30:31], v[182:183] op_sel_hi:[1,0]
	v_pk_mul_f32 v[32:33], v[32:33], v[182:183] op_sel_hi:[1,0]
	v_add_f32_e32 v116, 1.0, v116
	v_add_f32_e32 v117, 1.0, v117
	v_rcp_f32_e32 v116, v116
	v_rcp_f32_e32 v117, v117
	v_pk_mul_f32 v[26:27], v[26:27], v[182:183] op_sel_hi:[1,0]
	v_pk_mul_f32 v[22:23], v[22:23], v[182:183] op_sel_hi:[1,0]
	v_pk_mul_f32 v[24:25], v[24:25], v[182:183] op_sel_hi:[1,0]
	v_pk_mul_f32 v[114:115], v[114:115], v[116:117]
	v_pk_mul_f32 v[18:19], v[18:19], v[134:135] op_sel_hi:[1,0]
	v_pk_mul_f32 v[112:113], v[112:113], v[114:115]
	v_mul_f32_e32 v114, 0xbfb8aa3b, v106
	v_mul_f32_e32 v115, 0xbfb8aa3b, v107
	v_exp_f32_e32 v114, v114
	v_exp_f32_e32 v115, v115
	v_pk_mul_f32 v[10:11], v[10:11], v[134:135] op_sel_hi:[1,0]
	v_pk_mul_f32 v[12:13], v[12:13], v[134:135] op_sel_hi:[1,0]
	v_add_f32_e32 v114, 1.0, v114
	v_add_f32_e32 v115, 1.0, v115
	v_rcp_f32_e32 v114, v114
	v_rcp_f32_e32 v115, v115
	v_pk_mul_f32 v[6:7], v[6:7], v[134:135] op_sel_hi:[1,0]
	v_pk_mul_f32 v[2:3], v[2:3], v[134:135] op_sel_hi:[1,0]
	v_pk_mul_f32 v[4:5], v[4:5], v[134:135] op_sel_hi:[1,0]
	v_pk_mul_f32 v[106:107], v[106:107], v[114:115]
	v_mad_u64_u32 v[114:115], s[2:3], v160, s78, v[136:137]
	v_pk_mul_f32 v[106:107], v[102:103], v[106:107]
	v_pk_mul_f32 v[102:103], v[108:109], v[170:171] op_sel_hi:[1,0]
	s_mov_b64 s[4:5], -1
	v_mul_f32_e32 v108, 0xbfb8aa3b, v102
	v_mul_f32_e32 v109, 0xbfb8aa3b, v103
	v_exp_f32_e32 v108, v108
	v_exp_f32_e32 v109, v109
	s_andn2_b64 vcc, exec, s[0:1]
	v_add_f32_e32 v108, 1.0, v108
	v_add_f32_e32 v109, 1.0, v109
	v_rcp_f32_e32 v108, v108
	v_rcp_f32_e32 v109, v109
	s_nop 0
	v_pk_mul_f32 v[102:103], v[102:103], v[108:109]
	s_nop 0
	v_pk_mul_f32 v[108:109], v[104:105], v[102:103]
	v_mov_b32_e32 v102, v115
	v_mad_u64_u32 v[102:103], s[2:3], v161, s78, v[102:103]
	v_mov_b32_e32 v115, v102
	v_cvt_pk_bf16_f32 v102, v110, v111
	v_cvt_pk_bf16_f32 v103, v112, v113
	v_cvt_pk_bf16_f32 v104, v106, v107
	v_cvt_pk_bf16_f32 v105, v108, v109
	global_store_dwordx4 v[114:115], v[102:105], off sc1
	s_nop 1
	v_mul_f32_e32 v102, 0xbfb8aa3b, v98
	v_mul_f32_e32 v103, 0xbfb8aa3b, v99
	v_exp_f32_e32 v102, v102
	v_exp_f32_e32 v103, v103
	v_add_f32_e32 v102, 1.0, v102
	v_add_f32_e32 v103, 1.0, v103
	v_rcp_f32_e32 v102, v102
	v_rcp_f32_e32 v103, v103
	s_nop 0
	v_pk_mul_f32 v[98:99], v[98:99], v[102:103]
	s_nop 0
	v_pk_mul_f32 v[94:95], v[94:95], v[98:99]
	v_pk_mul_f32 v[98:99], v[100:101], v[168:169] op_sel_hi:[1,0]
	s_nop 0
	v_mul_f32_e32 v100, 0xbfb8aa3b, v98
	v_mul_f32_e32 v101, 0xbfb8aa3b, v99
	v_exp_f32_e32 v100, v100
	v_exp_f32_e32 v101, v101
	v_add_f32_e32 v100, 1.0, v100
	v_add_f32_e32 v101, 1.0, v101
	v_rcp_f32_e32 v100, v100
	v_rcp_f32_e32 v101, v101
	s_nop 0
	v_pk_mul_f32 v[98:99], v[98:99], v[100:101]
	s_nop 0
	v_pk_mul_f32 v[96:97], v[96:97], v[98:99]
	v_mul_f32_e32 v98, 0xbfb8aa3b, v90
	v_mul_f32_e32 v99, 0xbfb8aa3b, v91
	v_exp_f32_e32 v98, v98
	v_exp_f32_e32 v99, v99
	v_add_f32_e32 v98, 1.0, v98
	v_add_f32_e32 v99, 1.0, v99
	v_rcp_f32_e32 v98, v98
	v_rcp_f32_e32 v99, v99
	s_nop 0
	v_pk_mul_f32 v[90:91], v[90:91], v[98:99]
	s_nop 0
	v_pk_mul_f32 v[90:91], v[86:87], v[90:91]
	v_pk_mul_f32 v[86:87], v[92:93], v[168:169] op_sel_hi:[1,0]
	v_mad_u64_u32 v[98:99], s[2:3], v158, s78, v[136:137]
	v_mul_f32_e32 v92, 0xbfb8aa3b, v86
	v_mul_f32_e32 v93, 0xbfb8aa3b, v87
	v_exp_f32_e32 v92, v92
	v_exp_f32_e32 v93, v93
	v_add_f32_e32 v92, 1.0, v92
	v_add_f32_e32 v93, 1.0, v93
	v_rcp_f32_e32 v92, v92
	v_rcp_f32_e32 v93, v93
	s_nop 0
	v_pk_mul_f32 v[86:87], v[86:87], v[92:93]
	s_nop 0
	v_pk_mul_f32 v[92:93], v[88:89], v[86:87]
	v_mov_b32_e32 v86, v99
	v_mad_u64_u32 v[86:87], s[2:3], v159, s78, v[86:87]
	v_mov_b32_e32 v99, v86
	v_cvt_pk_bf16_f32 v86, v94, v95
	v_cvt_pk_bf16_f32 v87, v96, v97
	v_cvt_pk_bf16_f32 v88, v90, v91
	v_cvt_pk_bf16_f32 v89, v92, v93
	global_store_dwordx4 v[98:99], v[86:89], off sc1
	s_nop 1
	v_mul_f32_e32 v86, 0xbfb8aa3b, v82
	v_mul_f32_e32 v87, 0xbfb8aa3b, v83
	v_exp_f32_e32 v86, v86
	v_exp_f32_e32 v87, v87
	v_add_f32_e32 v86, 1.0, v86
	v_add_f32_e32 v87, 1.0, v87
	v_rcp_f32_e32 v86, v86
	v_rcp_f32_e32 v87, v87
	s_nop 0
	v_pk_mul_f32 v[82:83], v[82:83], v[86:87]
	s_nop 0
	v_pk_mul_f32 v[78:79], v[78:79], v[82:83]
	v_pk_mul_f32 v[82:83], v[84:85], v[164:165] op_sel_hi:[1,0]
	s_nop 0
	v_mul_f32_e32 v84, 0xbfb8aa3b, v82
	v_mul_f32_e32 v85, 0xbfb8aa3b, v83
	v_exp_f32_e32 v84, v84
	v_exp_f32_e32 v85, v85
	v_add_f32_e32 v84, 1.0, v84
	v_add_f32_e32 v85, 1.0, v85
	v_rcp_f32_e32 v84, v84
	v_rcp_f32_e32 v85, v85
	s_nop 0
	v_pk_mul_f32 v[82:83], v[82:83], v[84:85]
	s_nop 0
	v_pk_mul_f32 v[80:81], v[80:81], v[82:83]
	v_mul_f32_e32 v82, 0xbfb8aa3b, v74
	v_mul_f32_e32 v83, 0xbfb8aa3b, v75
	v_exp_f32_e32 v82, v82
	v_exp_f32_e32 v83, v83
	v_add_f32_e32 v82, 1.0, v82
	v_add_f32_e32 v83, 1.0, v83
	v_rcp_f32_e32 v82, v82
	v_rcp_f32_e32 v83, v83
	s_nop 0
	v_pk_mul_f32 v[74:75], v[74:75], v[82:83]
	s_nop 0
	v_pk_mul_f32 v[74:75], v[70:71], v[74:75]
	v_pk_mul_f32 v[70:71], v[76:77], v[164:165] op_sel_hi:[1,0]
	v_mad_u64_u32 v[82:83], s[2:3], v156, s78, v[136:137]
	v_mul_f32_e32 v76, 0xbfb8aa3b, v70
	v_mul_f32_e32 v77, 0xbfb8aa3b, v71
	v_exp_f32_e32 v76, v76
	v_exp_f32_e32 v77, v77
	v_add_f32_e32 v76, 1.0, v76
	v_add_f32_e32 v77, 1.0, v77
	v_rcp_f32_e32 v76, v76
	v_rcp_f32_e32 v77, v77
	s_nop 0
	v_pk_mul_f32 v[70:71], v[70:71], v[76:77]
	s_nop 0
	v_pk_mul_f32 v[76:77], v[72:73], v[70:71]
	v_mov_b32_e32 v70, v83
	v_mad_u64_u32 v[70:71], s[2:3], v157, s78, v[70:71]
	v_mov_b32_e32 v83, v70
	v_cvt_pk_bf16_f32 v70, v78, v79
	v_cvt_pk_bf16_f32 v71, v80, v81
	v_cvt_pk_bf16_f32 v72, v74, v75
	v_cvt_pk_bf16_f32 v73, v76, v77
	global_store_dwordx4 v[82:83], v[70:73], off sc1
	s_nop 1
	v_mul_f32_e32 v70, 0xbfb8aa3b, v66
	v_mul_f32_e32 v71, 0xbfb8aa3b, v67
	v_exp_f32_e32 v70, v70
	v_exp_f32_e32 v71, v71
	v_add_f32_e32 v70, 1.0, v70
	v_add_f32_e32 v71, 1.0, v71
	v_rcp_f32_e32 v70, v70
	v_rcp_f32_e32 v71, v71
	s_nop 0
	v_pk_mul_f32 v[66:67], v[66:67], v[70:71]
	s_nop 0
	v_pk_mul_f32 v[62:63], v[62:63], v[66:67]
	v_pk_mul_f32 v[66:67], v[68:69], v[166:167] op_sel_hi:[1,0]
	s_nop 0
	v_mul_f32_e32 v68, 0xbfb8aa3b, v66
	v_mul_f32_e32 v69, 0xbfb8aa3b, v67
	v_exp_f32_e32 v68, v68
	v_exp_f32_e32 v69, v69
	v_add_f32_e32 v68, 1.0, v68
	v_add_f32_e32 v69, 1.0, v69
	v_rcp_f32_e32 v68, v68
	v_rcp_f32_e32 v69, v69
	s_nop 0
	v_pk_mul_f32 v[66:67], v[66:67], v[68:69]
	s_nop 0
	v_pk_mul_f32 v[64:65], v[64:65], v[66:67]
	v_mul_f32_e32 v66, 0xbfb8aa3b, v58
	v_mul_f32_e32 v67, 0xbfb8aa3b, v59
	v_exp_f32_e32 v66, v66
	v_exp_f32_e32 v67, v67
	v_add_f32_e32 v66, 1.0, v66
	v_add_f32_e32 v67, 1.0, v67
	v_rcp_f32_e32 v66, v66
	v_rcp_f32_e32 v67, v67
	s_nop 0
	v_pk_mul_f32 v[58:59], v[58:59], v[66:67]
	s_nop 0
	v_pk_mul_f32 v[58:59], v[54:55], v[58:59]
	v_pk_mul_f32 v[54:55], v[60:61], v[166:167] op_sel_hi:[1,0]
	v_mad_u64_u32 v[66:67], s[2:3], v154, s78, v[136:137]
	v_mul_f32_e32 v60, 0xbfb8aa3b, v54
	v_mul_f32_e32 v61, 0xbfb8aa3b, v55
	v_exp_f32_e32 v60, v60
	v_exp_f32_e32 v61, v61
	v_add_f32_e32 v60, 1.0, v60
	v_add_f32_e32 v61, 1.0, v61
	v_rcp_f32_e32 v60, v60
	v_rcp_f32_e32 v61, v61
	s_nop 0
	v_pk_mul_f32 v[54:55], v[54:55], v[60:61]
	s_nop 0
	v_pk_mul_f32 v[60:61], v[56:57], v[54:55]
	v_mov_b32_e32 v54, v67
	v_mad_u64_u32 v[54:55], s[2:3], v155, s78, v[54:55]
	v_mov_b32_e32 v67, v54
	v_cvt_pk_bf16_f32 v54, v62, v63
	v_cvt_pk_bf16_f32 v55, v64, v65
	v_cvt_pk_bf16_f32 v56, v58, v59
	v_cvt_pk_bf16_f32 v57, v60, v61
	global_store_dwordx4 v[66:67], v[54:57], off sc1
	s_nop 1
	v_mul_f32_e32 v54, 0xbfb8aa3b, v50
	v_mul_f32_e32 v55, 0xbfb8aa3b, v51
	v_exp_f32_e32 v54, v54
	v_exp_f32_e32 v55, v55
	v_add_f32_e32 v54, 1.0, v54
	v_add_f32_e32 v55, 1.0, v55
	v_rcp_f32_e32 v54, v54
	v_rcp_f32_e32 v55, v55
	s_nop 0
	v_pk_mul_f32 v[50:51], v[50:51], v[54:55]
	s_nop 0
	v_pk_mul_f32 v[46:47], v[46:47], v[50:51]
	v_pk_mul_f32 v[50:51], v[52:53], v[174:175] op_sel_hi:[1,0]
	s_nop 0
	v_mul_f32_e32 v52, 0xbfb8aa3b, v50
	v_mul_f32_e32 v53, 0xbfb8aa3b, v51
	v_exp_f32_e32 v52, v52
	v_exp_f32_e32 v53, v53
	v_add_f32_e32 v52, 1.0, v52
	v_add_f32_e32 v53, 1.0, v53
	v_rcp_f32_e32 v52, v52
	v_rcp_f32_e32 v53, v53
	s_nop 0
	v_pk_mul_f32 v[50:51], v[50:51], v[52:53]
	s_nop 0
	v_pk_mul_f32 v[48:49], v[48:49], v[50:51]
	v_mul_f32_e32 v50, 0xbfb8aa3b, v42
	v_mul_f32_e32 v51, 0xbfb8aa3b, v43
	v_exp_f32_e32 v50, v50
	v_exp_f32_e32 v51, v51
	v_add_f32_e32 v50, 1.0, v50
	v_add_f32_e32 v51, 1.0, v51
	v_rcp_f32_e32 v50, v50
	v_rcp_f32_e32 v51, v51
	s_nop 0
	v_pk_mul_f32 v[42:43], v[42:43], v[50:51]
	s_nop 0
	v_pk_mul_f32 v[42:43], v[38:39], v[42:43]
	v_pk_mul_f32 v[38:39], v[44:45], v[174:175] op_sel_hi:[1,0]
	v_mad_u64_u32 v[50:51], s[2:3], v152, s78, v[136:137]
	v_mul_f32_e32 v44, 0xbfb8aa3b, v38
	v_mul_f32_e32 v45, 0xbfb8aa3b, v39
	v_exp_f32_e32 v44, v44
	v_exp_f32_e32 v45, v45
	v_add_f32_e32 v44, 1.0, v44
	v_add_f32_e32 v45, 1.0, v45
	v_rcp_f32_e32 v44, v44
	v_rcp_f32_e32 v45, v45
	s_nop 0
	v_pk_mul_f32 v[38:39], v[38:39], v[44:45]
	s_nop 0
	v_pk_mul_f32 v[44:45], v[40:41], v[38:39]
	v_mov_b32_e32 v38, v51
	v_mad_u64_u32 v[38:39], s[2:3], v153, s78, v[38:39]
	v_mov_b32_e32 v51, v38
	v_cvt_pk_bf16_f32 v38, v46, v47
	v_cvt_pk_bf16_f32 v39, v48, v49
	v_cvt_pk_bf16_f32 v40, v42, v43
	v_cvt_pk_bf16_f32 v41, v44, v45
	global_store_dwordx4 v[50:51], v[38:41], off sc1
	s_nop 1
	v_mul_f32_e32 v38, 0xbfb8aa3b, v34
	v_mul_f32_e32 v39, 0xbfb8aa3b, v35
	v_exp_f32_e32 v38, v38
	v_exp_f32_e32 v39, v39
	v_add_f32_e32 v38, 1.0, v38
	v_add_f32_e32 v39, 1.0, v39
	v_rcp_f32_e32 v38, v38
	v_rcp_f32_e32 v39, v39
	s_nop 0
	v_pk_mul_f32 v[34:35], v[34:35], v[38:39]
	s_nop 0
	v_pk_mul_f32 v[30:31], v[30:31], v[34:35]
	v_pk_mul_f32 v[34:35], v[36:37], v[182:183] op_sel_hi:[1,0]
	s_nop 0
	v_mul_f32_e32 v36, 0xbfb8aa3b, v34
	v_mul_f32_e32 v37, 0xbfb8aa3b, v35
	v_exp_f32_e32 v36, v36
	v_exp_f32_e32 v37, v37
	v_add_f32_e32 v36, 1.0, v36
	v_add_f32_e32 v37, 1.0, v37
	v_rcp_f32_e32 v36, v36
	v_rcp_f32_e32 v37, v37
	s_nop 0
	v_pk_mul_f32 v[34:35], v[34:35], v[36:37]
	s_nop 0
	v_pk_mul_f32 v[32:33], v[32:33], v[34:35]
	v_mul_f32_e32 v34, 0xbfb8aa3b, v26
	v_mul_f32_e32 v35, 0xbfb8aa3b, v27
	v_exp_f32_e32 v34, v34
	v_exp_f32_e32 v35, v35
	v_add_f32_e32 v34, 1.0, v34
	v_add_f32_e32 v35, 1.0, v35
	v_rcp_f32_e32 v34, v34
	v_rcp_f32_e32 v35, v35
	s_nop 0
	v_pk_mul_f32 v[26:27], v[26:27], v[34:35]
	s_nop 0
	v_pk_mul_f32 v[26:27], v[22:23], v[26:27]
	v_pk_mul_f32 v[22:23], v[28:29], v[182:183] op_sel_hi:[1,0]
	v_mad_u64_u32 v[34:35], s[2:3], v150, s78, v[136:137]
	v_mul_f32_e32 v28, 0xbfb8aa3b, v22
	v_mul_f32_e32 v29, 0xbfb8aa3b, v23
	v_exp_f32_e32 v28, v28
	v_exp_f32_e32 v29, v29
	v_add_f32_e32 v28, 1.0, v28
	v_add_f32_e32 v29, 1.0, v29
	v_rcp_f32_e32 v28, v28
	v_rcp_f32_e32 v29, v29
	s_nop 0
	v_pk_mul_f32 v[22:23], v[22:23], v[28:29]
	s_nop 0
	v_pk_mul_f32 v[28:29], v[24:25], v[22:23]
	v_mov_b32_e32 v22, v35
	v_mad_u64_u32 v[22:23], s[2:3], v151, s78, v[22:23]
	v_mov_b32_e32 v35, v22
	v_cvt_pk_bf16_f32 v22, v30, v31
	v_cvt_pk_bf16_f32 v23, v32, v33
	v_cvt_pk_bf16_f32 v24, v26, v27
	v_cvt_pk_bf16_f32 v25, v28, v29
	global_store_dwordx4 v[34:35], v[22:25], off sc1
	s_nop 1
	v_mul_f32_e32 v22, 0xbfb8aa3b, v18
	v_mul_f32_e32 v23, 0xbfb8aa3b, v19
	v_exp_f32_e32 v22, v22
	v_exp_f32_e32 v23, v23
	v_add_f32_e32 v22, 1.0, v22
	v_add_f32_e32 v23, 1.0, v23
	v_rcp_f32_e32 v22, v22
	v_rcp_f32_e32 v23, v23
	s_nop 0
	v_pk_mul_f32 v[18:19], v[18:19], v[22:23]
	s_nop 0
	v_pk_mul_f32 v[10:11], v[10:11], v[18:19]
	v_pk_mul_f32 v[18:19], v[20:21], v[134:135] op_sel_hi:[1,0]
	s_nop 0
	v_mul_f32_e32 v20, 0xbfb8aa3b, v18
	v_mul_f32_e32 v21, 0xbfb8aa3b, v19
	v_exp_f32_e32 v20, v20
	v_exp_f32_e32 v21, v21
	v_add_f32_e32 v20, 1.0, v20
	v_add_f32_e32 v21, 1.0, v21
	v_rcp_f32_e32 v20, v20
	v_rcp_f32_e32 v21, v21
	s_nop 0
	v_pk_mul_f32 v[18:19], v[18:19], v[20:21]
	s_nop 0
	v_pk_mul_f32 v[12:13], v[12:13], v[18:19]
	v_mul_f32_e32 v18, 0xbfb8aa3b, v6
	v_mul_f32_e32 v19, 0xbfb8aa3b, v7
	v_exp_f32_e32 v18, v18
	v_exp_f32_e32 v19, v19
	v_add_f32_e32 v18, 1.0, v18
	v_add_f32_e32 v19, 1.0, v19
	v_rcp_f32_e32 v18, v18
	v_rcp_f32_e32 v19, v19
	s_nop 0
	v_pk_mul_f32 v[6:7], v[6:7], v[18:19]
	s_nop 0
	v_pk_mul_f32 v[6:7], v[2:3], v[6:7]
	v_pk_mul_f32 v[2:3], v[8:9], v[134:135] op_sel_hi:[1,0]
	v_mad_u64_u32 v[18:19], s[2:3], v148, s78, v[136:137]
	v_mul_f32_e32 v8, 0xbfb8aa3b, v2
	v_mul_f32_e32 v9, 0xbfb8aa3b, v3
	v_exp_f32_e32 v8, v8
	v_exp_f32_e32 v9, v9
	v_add_f32_e32 v8, 1.0, v8
	v_add_f32_e32 v9, 1.0, v9
	v_rcp_f32_e32 v8, v8
	v_rcp_f32_e32 v9, v9
	s_nop 0
	v_pk_mul_f32 v[2:3], v[2:3], v[8:9]
	s_nop 0
	v_pk_mul_f32 v[8:9], v[4:5], v[2:3]
	v_mov_b32_e32 v2, v19
	v_mad_u64_u32 v[2:3], s[2:3], v149, s78, v[2:3]
	v_mov_b32_e32 v19, v2
	v_cvt_pk_bf16_f32 v2, v10, v11
	v_cvt_pk_bf16_f32 v3, v12, v13
	v_cvt_pk_bf16_f32 v4, v6, v7
	v_cvt_pk_bf16_f32 v5, v8, v9
	global_store_dwordx4 v[18:19], v[2:5], off sc1
	s_cbranch_vccnz .LBB0_889
	s_andn2_b64 vcc, exec, s[6:7]
	s_cbranch_vccnz .LBB0_888
	s_barrier
	s_branch .LBB0_888
